# bias_rows: the three wave-sum reduction chains per output interleaved (6 LDS round trips instead of 18), one store block
# speedup vs baseline: 1.0044x; 1.0044x over previous
; __device__ __forceinline__ float wave_sum(float v) {
; #pragma unroll
;     for (int o = 1; o < 64; o <<= 1) v += __shfl_xor(v, o);
;     return v;
; }
; __device__ __forceinline__ void bias_rows(const bf16_t* Wt, int N, const float* sh  , float* bias  , int gwi, int ngw, int lane) {
;     ...
;     for (int n = gwi; n < N; n += ngw) {
;         const u32x4 w0 = *(const u32x4*)(Wt + (size_t)n * DM + 8 * lane), w1 = *(const u32x4*)(Wt + (size_t)n * DM + 512 + 8 * lane);
;         float wf[16];
; #pragma unroll
;         for (int j = 0; j < 4; ++j) { wf[2 * j] = __uint_as_float(w0[j] << 16); wf[2 * j + 1] = __uint_as_float(w0[j] & 0xffff0000u); wf[8 + 2 * j] = __uint_as_float(w1[j] << 16); wf[8 + 2 * j + 1] = __uint_as_float(w1[j] & 0xffff0000u); }
; #pragma unroll
;         for (int v = 0; v < 3; ++v) {
;             float a = 0.f;
; #pragma unroll
;             for (int j = 0; j < 16; ++j) a += wf[j] * s[v][j >> 2][j & 3];
;             a = wave_sum(a);
;             if (lane == 0) bias[(size_t)v * N + n] = a;
;         }
;     }
.LBB0_119:
	v_lshl_add_u64 v[58:59], s[92:93], 0, v[56:57]
	v_add_co_u32_e32 v58, vcc, 0x400000, v58
	s_nop 1
	v_addc_co_u32_e32 v59, vcc, 0, v59, vcc
	global_load_dwordx4 v[80:83], v[58:59], off
	global_load_dwordx4 v[84:87], v[58:59], off offset:1024
	s_waitcnt vmcnt(0)
	v_lshlrev_b32_e32 v79, 16, v80
	v_and_b32_e32 v75, 0xffff0000, v80
	v_fma_f32 v58, v40, v79, 0
	v_lshlrev_b32_e32 v80, 16, v81
	v_fmac_f32_e32 v58, v41, v75
	v_and_b32_e32 v76, 0xffff0000, v81
	v_fmac_f32_e32 v58, v42, v80
	v_lshlrev_b32_e32 v81, 16, v82
	v_fmac_f32_e32 v58, v43, v76
	v_and_b32_e32 v77, 0xffff0000, v82
	v_fmac_f32_e32 v58, v44, v81
	v_lshlrev_b32_e32 v82, 16, v83
	v_fmac_f32_e32 v58, v45, v77
	v_and_b32_e32 v78, 0xffff0000, v83
	v_fmac_f32_e32 v58, v46, v82
	v_lshlrev_b32_e32 v71, 16, v84
	v_fmac_f32_e32 v58, v47, v78
	v_and_b32_e32 v67, 0xffff0000, v84
	v_fmac_f32_e32 v58, v32, v71
	v_lshlrev_b32_e32 v72, 16, v85
	v_fmac_f32_e32 v58, v33, v67
	s_waitcnt lgkmcnt(0)
	v_and_b32_e32 v68, 0xffff0000, v85
	v_fmac_f32_e32 v58, v34, v72
	v_lshlrev_b32_e32 v73, 16, v86
	v_fmac_f32_e32 v58, v35, v68
	v_and_b32_e32 v69, 0xffff0000, v86
	v_fmac_f32_e32 v58, v36, v73
	v_lshlrev_b32_e32 v74, 16, v87
	v_fmac_f32_e32 v58, v37, v69
	v_and_b32_e32 v70, 0xffff0000, v87
	v_fmac_f32_e32 v58, v38, v74
	v_fmac_f32_e32 v58, v39, v70
	v_fma_f32 v120, v20, v79, 0
	v_fmac_f32_e32 v120, v21, v75
	v_fmac_f32_e32 v120, v22, v80
	v_fmac_f32_e32 v120, v23, v76
	v_fmac_f32_e32 v120, v28, v81
	v_fmac_f32_e32 v120, v29, v77
	v_fmac_f32_e32 v120, v30, v82
	v_fmac_f32_e32 v120, v31, v78
	v_fmac_f32_e32 v120, v24, v71
	v_fmac_f32_e32 v120, v25, v67
	v_fmac_f32_e32 v120, v26, v72
	v_fmac_f32_e32 v120, v27, v68
	v_fmac_f32_e32 v120, v16, v73
	v_fmac_f32_e32 v120, v17, v69
	v_fmac_f32_e32 v120, v18, v74
	v_fmac_f32_e32 v120, v19, v70
	v_fma_f32 v121, v4, v79, 0
	v_fmac_f32_e32 v121, v5, v75
	v_fmac_f32_e32 v121, v6, v80
	v_fmac_f32_e32 v121, v7, v76
	v_fmac_f32_e32 v121, v12, v81
	v_fmac_f32_e32 v121, v13, v77
	v_fmac_f32_e32 v121, v14, v82
	v_fmac_f32_e32 v121, v15, v78
	v_fmac_f32_e32 v121, v8, v71
	v_fmac_f32_e32 v121, v9, v67
	v_fmac_f32_e32 v121, v10, v72
	v_fmac_f32_e32 v121, v11, v68
	v_fmac_f32_e32 v121, v0, v73
	v_fmac_f32_e32 v121, v1, v69
	v_fmac_f32_e32 v121, v2, v74
	v_fmac_f32_e32 v121, v3, v70
	ds_bpermute_b32 v122, v53, v58
	ds_bpermute_b32 v123, v53, v120
	ds_bpermute_b32 v124, v53, v121
	s_waitcnt lgkmcnt(0)
	v_add_f32_e32 v58, v58, v122
	v_add_f32_e32 v120, v120, v123
	v_add_f32_e32 v121, v121, v124
	ds_bpermute_b32 v122, v61, v58
	ds_bpermute_b32 v123, v61, v120
	ds_bpermute_b32 v124, v61, v121
	s_waitcnt lgkmcnt(0)
	v_add_f32_e32 v58, v58, v122
	v_add_f32_e32 v120, v120, v123
	v_add_f32_e32 v121, v121, v124
	ds_bpermute_b32 v122, v62, v58
	ds_bpermute_b32 v123, v62, v120
	ds_bpermute_b32 v124, v62, v121
	s_waitcnt lgkmcnt(0)
	v_add_f32_e32 v58, v58, v122
	v_add_f32_e32 v120, v120, v123
	v_add_f32_e32 v121, v121, v124
	ds_bpermute_b32 v122, v63, v58
	ds_bpermute_b32 v123, v63, v120
	ds_bpermute_b32 v124, v63, v121
	s_waitcnt lgkmcnt(0)
	v_add_f32_e32 v58, v58, v122
	v_add_f32_e32 v120, v120, v123
	v_add_f32_e32 v121, v121, v124
	ds_bpermute_b32 v122, v64, v58
	ds_bpermute_b32 v123, v64, v120
	ds_bpermute_b32 v124, v64, v121
	s_waitcnt lgkmcnt(0)
	v_add_f32_e32 v58, v58, v122
	v_add_f32_e32 v120, v120, v123
	v_add_f32_e32 v121, v121, v124
	ds_bpermute_b32 v122, v65, v58
	ds_bpermute_b32 v123, v65, v120
	ds_bpermute_b32 v124, v65, v121
	s_waitcnt lgkmcnt(0)
	v_add_f32_e32 v58, v58, v122
	v_add_f32_e32 v120, v120, v123
	v_add_f32_e32 v121, v121, v124
	v_lshl_add_u64 v[126:127], s[92:93], 0, v[54:55]
	s_and_saveexec_b64 s[12:13], s[0:1]
	s_cbranch_execz .LBB0_118
	v_add_co_u32_e32 v128, vcc, 0x48000, v126
	s_nop 1
	v_addc_co_u32_e32 v129, vcc, 0, v127, vcc
	global_store_dword v[128:129], v58, off
	v_add_co_u32_e32 v128, vcc, 0x4a000, v126
	s_nop 1
	v_addc_co_u32_e32 v129, vcc, 0, v127, vcc
	global_store_dword v[128:129], v120, off offset:1024
	v_add_co_u32_e32 v128, vcc, 0x4c000, v126
	s_nop 1
	v_addc_co_u32_e32 v129, vcc, 0, v127, vcc
	global_store_dword v[128:129], v121, off offset:2048
	s_branch .LBB0_118

; __device__ __forceinline__ float wave_sum(float v) {
; #pragma unroll
;     for (int o = 1; o < 64; o <<= 1) v += __shfl_xor(v, o);
;     return v;
; }
; __device__ __forceinline__ void bias_rows(const bf16_t* Wt, int N, const float* sh  , float* bias  , int gwi, int ngw, int lane) {
;     ...
;     for (int n = gwi; n < N; n += ngw) {
;         const u32x4 w0 = *(const u32x4*)(Wt + (size_t)n * DM + 8 * lane), w1 = *(const u32x4*)(Wt + (size_t)n * DM + 512 + 8 * lane);
;         float wf[16];
; #pragma unroll
;         for (int j = 0; j < 4; ++j) { wf[2 * j] = __uint_as_float(w0[j] << 16); wf[2 * j + 1] = __uint_as_float(w0[j] & 0xffff0000u); wf[8 + 2 * j] = __uint_as_float(w1[j] << 16); wf[8 + 2 * j + 1] = __uint_as_float(w1[j] & 0xffff0000u); }
; #pragma unroll
;         for (int v = 0; v < 3; ++v) {
;             float a = 0.f;
; #pragma unroll
;             for (int j = 0; j < 16; ++j) a += wf[j] * s[v][j >> 2][j & 3];
;             a = wave_sum(a);
;             if (lane == 0) bias[(size_t)v * N + n] = a;
;         }
;     }
.LBB0_128:
	v_lshl_add_u64 v[56:57], s[92:93], 0, v[54:55]
	v_add_co_u32_e32 v56, vcc, 0xa80000, v56
	s_nop 1
	v_addc_co_u32_e32 v57, vcc, 0, v57, vcc
	global_load_dwordx4 v[78:81], v[56:57], off
	global_load_dwordx4 v[82:85], v[56:57], off offset:1024
	s_waitcnt vmcnt(0)
	v_lshlrev_b32_e32 v77, 16, v78
	v_and_b32_e32 v73, 0xffff0000, v78
	v_fma_f32 v56, v36, v77, 0
	v_lshlrev_b32_e32 v78, 16, v79
	v_fmac_f32_e32 v56, v37, v73
	v_and_b32_e32 v74, 0xffff0000, v79
	v_fmac_f32_e32 v56, v38, v78
	v_lshlrev_b32_e32 v79, 16, v80
	v_fmac_f32_e32 v56, v39, v74
	v_and_b32_e32 v75, 0xffff0000, v80
	v_fmac_f32_e32 v56, v44, v79
	v_lshlrev_b32_e32 v80, 16, v81
	v_fmac_f32_e32 v56, v45, v75
	v_and_b32_e32 v76, 0xffff0000, v81
	v_fmac_f32_e32 v56, v46, v80
	v_lshlrev_b32_e32 v69, 16, v82
	v_fmac_f32_e32 v56, v47, v76
	v_and_b32_e32 v65, 0xffff0000, v82
	v_fmac_f32_e32 v56, v40, v69
	v_lshlrev_b32_e32 v70, 16, v83
	v_fmac_f32_e32 v56, v41, v65
	s_waitcnt lgkmcnt(0)
	v_and_b32_e32 v66, 0xffff0000, v83
	v_fmac_f32_e32 v56, v42, v70
	v_lshlrev_b32_e32 v71, 16, v84
	v_fmac_f32_e32 v56, v43, v66
	v_and_b32_e32 v67, 0xffff0000, v84
	v_fmac_f32_e32 v56, v28, v71
	v_lshlrev_b32_e32 v72, 16, v85
	v_fmac_f32_e32 v56, v29, v67
	s_waitcnt lgkmcnt(0)
	v_and_b32_e32 v68, 0xffff0000, v85
	v_fmac_f32_e32 v56, v30, v72
	v_fmac_f32_e32 v56, v31, v68
	v_fma_f32 v120, v20, v77, 0
	v_fmac_f32_e32 v120, v21, v73
	v_fmac_f32_e32 v120, v22, v78
	v_fmac_f32_e32 v120, v23, v74
	v_fmac_f32_e32 v120, v32, v79
	v_fmac_f32_e32 v120, v33, v75
	v_fmac_f32_e32 v120, v34, v80
	v_fmac_f32_e32 v120, v35, v76
	v_fmac_f32_e32 v120, v16, v69
	v_fmac_f32_e32 v120, v17, v65
	v_fmac_f32_e32 v120, v18, v70
	v_fmac_f32_e32 v120, v19, v66
	v_fmac_f32_e32 v120, v12, v71
	v_fmac_f32_e32 v120, v13, v67
	v_fmac_f32_e32 v120, v14, v72
	v_fmac_f32_e32 v120, v15, v68
	v_fma_f32 v121, v4, v77, 0
	v_fmac_f32_e32 v121, v5, v73
	v_fmac_f32_e32 v121, v6, v78
	v_fmac_f32_e32 v121, v7, v74
	v_fmac_f32_e32 v121, v8, v79
	v_fmac_f32_e32 v121, v9, v75
	v_fmac_f32_e32 v121, v10, v80
	v_fmac_f32_e32 v121, v11, v76
	v_fmac_f32_e32 v121, v0, v69
	v_fmac_f32_e32 v121, v1, v65
	v_fmac_f32_e32 v121, v2, v70
	v_fmac_f32_e32 v121, v3, v66
	v_fmac_f32_e32 v121, v24, v71
	v_fmac_f32_e32 v121, v25, v67
	v_fmac_f32_e32 v121, v26, v72
	v_fmac_f32_e32 v121, v27, v68
	ds_bpermute_b32 v122, v58, v56
	ds_bpermute_b32 v123, v58, v120
	ds_bpermute_b32 v124, v58, v121
	s_waitcnt lgkmcnt(0)
	v_add_f32_e32 v56, v56, v122
	v_add_f32_e32 v120, v120, v123
	v_add_f32_e32 v121, v121, v124
	ds_bpermute_b32 v122, v59, v56
	ds_bpermute_b32 v123, v59, v120
	ds_bpermute_b32 v124, v59, v121
	s_waitcnt lgkmcnt(0)
	v_add_f32_e32 v56, v56, v122
	v_add_f32_e32 v120, v120, v123
	v_add_f32_e32 v121, v121, v124
	ds_bpermute_b32 v122, v61, v56
	ds_bpermute_b32 v123, v61, v120
	ds_bpermute_b32 v124, v61, v121
	s_waitcnt lgkmcnt(0)
	v_add_f32_e32 v56, v56, v122
	v_add_f32_e32 v120, v120, v123
	v_add_f32_e32 v121, v121, v124
	ds_bpermute_b32 v122, v62, v56
	ds_bpermute_b32 v123, v62, v120
	ds_bpermute_b32 v124, v62, v121
	s_waitcnt lgkmcnt(0)
	v_add_f32_e32 v56, v56, v122
	v_add_f32_e32 v120, v120, v123
	v_add_f32_e32 v121, v121, v124
	ds_bpermute_b32 v122, v63, v56
	ds_bpermute_b32 v123, v63, v120
	ds_bpermute_b32 v124, v63, v121
	s_waitcnt lgkmcnt(0)
	v_add_f32_e32 v56, v56, v122
	v_add_f32_e32 v120, v120, v123
	v_add_f32_e32 v121, v121, v124
	ds_bpermute_b32 v122, v64, v56
	ds_bpermute_b32 v123, v64, v120
	ds_bpermute_b32 v124, v64, v121
	s_waitcnt lgkmcnt(0)
	v_add_f32_e32 v56, v56, v122
	v_add_f32_e32 v120, v120, v123
	v_add_f32_e32 v121, v121, v124
	v_lshl_add_u64 v[126:127], s[92:93], 0, v[52:53]
	s_and_saveexec_b64 s[12:13], s[0:1]
	s_cbranch_execz .LBB0_127
	v_add_co_u32_e32 v128, vcc, 0x63000, v126
	s_nop 1
	v_addc_co_u32_e32 v129, vcc, 0, v127, vcc
	global_store_dword v[128:129], v56, off
	v_add_co_u32_e32 v128, vcc, 0x68000, v126
	s_nop 1
	v_addc_co_u32_e32 v129, vcc, 0, v127, vcc
	global_store_dword v[128:129], v120, off offset:2048
	v_add_co_u32_e32 v128, vcc, 0x6e000, v126
	s_nop 1
	v_addc_co_u32_e32 v129, vcc, 0, v127, vcc
	global_store_dword v[128:129], v121, off
	s_branch .LBB0_127

; __device__ __forceinline__ float wave_sum(float v) {
; #pragma unroll
;     for (int o = 1; o < 64; o <<= 1) v += __shfl_xor(v, o);
;     return v;
; }
; __device__ __forceinline__ void bias_rows(const bf16_t* Wt, int N, const float* sh  , float* bias  , int gwi, int ngw, int lane) {
;     ...
;     for (int n = gwi; n < N; n += ngw) {
;         const u32x4 w0 = *(const u32x4*)(Wt + (size_t)n * DM + 8 * lane), w1 = *(const u32x4*)(Wt + (size_t)n * DM + 512 + 8 * lane);
;         float wf[16];
; #pragma unroll
;         for (int j = 0; j < 4; ++j) { wf[2 * j] = __uint_as_float(w0[j] << 16); wf[2 * j + 1] = __uint_as_float(w0[j] & 0xffff0000u); wf[8 + 2 * j] = __uint_as_float(w1[j] << 16); wf[8 + 2 * j + 1] = __uint_as_float(w1[j] & 0xffff0000u); }
; #pragma unroll
;         for (int v = 0; v < 3; ++v) {
;             float a = 0.f;
; #pragma unroll
;             for (int j = 0; j < 16; ++j) a += wf[j] * s[v][j >> 2][j & 3];
;             a = wave_sum(a);
;             if (lane == 0) bias[(size_t)v * N + n] = a;
;         }
;     }
.LBB0_1101:
	s_waitcnt lgkmcnt(0)
	global_load_dwordx4 v[64:67], v[52:53], off offset:-1024
	global_load_dwordx4 v[78:81], v[52:53], off
	s_waitcnt vmcnt(0)
	v_lshlrev_b32_e32 v76, 16, v64
	v_and_b32_e32 v72, 0xffff0000, v64
	v_fma_f32 v54, v40, v76, 0
	v_lshlrev_b32_e32 v77, 16, v65
	v_fmac_f32_e32 v54, v41, v72
	v_and_b32_e32 v73, 0xffff0000, v65
	v_fmac_f32_e32 v54, v42, v77
	v_lshlrev_b32_e32 v68, 16, v78
	v_and_b32_e32 v64, 0xffff0000, v78
	v_lshlrev_b32_e32 v78, 16, v66
	v_fmac_f32_e32 v54, v43, v73
	v_and_b32_e32 v74, 0xffff0000, v66
	v_fmac_f32_e32 v54, v44, v78
	v_lshlrev_b32_e32 v69, 16, v79
	v_and_b32_e32 v65, 0xffff0000, v79
	v_lshlrev_b32_e32 v79, 16, v67
	v_fmac_f32_e32 v54, v45, v74
	v_and_b32_e32 v75, 0xffff0000, v67
	v_fmac_f32_e32 v54, v46, v79
	v_fmac_f32_e32 v54, v47, v75
	v_fmac_f32_e32 v54, v32, v68
	v_fmac_f32_e32 v54, v33, v64
	v_fmac_f32_e32 v54, v34, v69
	v_lshlrev_b32_e32 v70, 16, v80
	v_fmac_f32_e32 v54, v35, v65
	v_and_b32_e32 v66, 0xffff0000, v80
	v_fmac_f32_e32 v54, v36, v70
	v_lshlrev_b32_e32 v71, 16, v81
	v_fmac_f32_e32 v54, v37, v66
	v_and_b32_e32 v67, 0xffff0000, v81
	v_fmac_f32_e32 v54, v38, v71
	v_fmac_f32_e32 v54, v39, v67
	v_fma_f32 v120, v20, v76, 0
	v_fmac_f32_e32 v120, v21, v72
	v_fmac_f32_e32 v120, v22, v77
	v_fmac_f32_e32 v120, v23, v73
	v_fmac_f32_e32 v120, v28, v78
	v_fmac_f32_e32 v120, v29, v74
	v_fmac_f32_e32 v120, v30, v79
	v_fmac_f32_e32 v120, v31, v75
	v_fmac_f32_e32 v120, v24, v68
	v_fmac_f32_e32 v120, v25, v64
	v_fmac_f32_e32 v120, v26, v69
	v_fmac_f32_e32 v120, v27, v65
	v_fmac_f32_e32 v120, v16, v70
	v_fmac_f32_e32 v120, v17, v66
	v_fmac_f32_e32 v120, v18, v71
	v_fmac_f32_e32 v120, v19, v67
	v_fma_f32 v121, v4, v76, 0
	v_fmac_f32_e32 v121, v5, v72
	v_fmac_f32_e32 v121, v6, v77
	v_fmac_f32_e32 v121, v7, v73
	v_fmac_f32_e32 v121, v12, v78
	v_fmac_f32_e32 v121, v13, v74
	v_fmac_f32_e32 v121, v14, v79
	v_fmac_f32_e32 v121, v15, v75
	v_fmac_f32_e32 v121, v8, v68
	v_fmac_f32_e32 v121, v9, v64
	v_fmac_f32_e32 v121, v10, v69
	v_fmac_f32_e32 v121, v11, v65
	v_fmac_f32_e32 v121, v0, v70
	v_fmac_f32_e32 v121, v1, v66
	v_fmac_f32_e32 v121, v2, v71
	v_fmac_f32_e32 v121, v3, v67
	ds_bpermute_b32 v122, v57, v54
	ds_bpermute_b32 v123, v57, v120
	ds_bpermute_b32 v124, v57, v121
	s_waitcnt lgkmcnt(0)
	v_add_f32_e32 v54, v54, v122
	v_add_f32_e32 v120, v120, v123
	v_add_f32_e32 v121, v121, v124
	ds_bpermute_b32 v122, v58, v54
	ds_bpermute_b32 v123, v58, v120
	ds_bpermute_b32 v124, v58, v121
	s_waitcnt lgkmcnt(0)
	v_add_f32_e32 v54, v54, v122
	v_add_f32_e32 v120, v120, v123
	v_add_f32_e32 v121, v121, v124
	ds_bpermute_b32 v122, v59, v54
	ds_bpermute_b32 v123, v59, v120
	ds_bpermute_b32 v124, v59, v121
	s_waitcnt lgkmcnt(0)
	v_add_f32_e32 v54, v54, v122
	v_add_f32_e32 v120, v120, v123
	v_add_f32_e32 v121, v121, v124
	ds_bpermute_b32 v122, v60, v54
	ds_bpermute_b32 v123, v60, v120
	ds_bpermute_b32 v124, v60, v121
	s_waitcnt lgkmcnt(0)
	v_add_f32_e32 v54, v54, v122
	v_add_f32_e32 v120, v120, v123
	v_add_f32_e32 v121, v121, v124
	ds_bpermute_b32 v122, v61, v54
	ds_bpermute_b32 v123, v61, v120
	ds_bpermute_b32 v124, v61, v121
	s_waitcnt lgkmcnt(0)
	v_add_f32_e32 v54, v54, v122
	v_add_f32_e32 v120, v120, v123
	v_add_f32_e32 v121, v121, v124
	ds_bpermute_b32 v122, v62, v54
	ds_bpermute_b32 v123, v62, v120
	ds_bpermute_b32 v124, v62, v121
	s_waitcnt lgkmcnt(0)
	v_add_f32_e32 v54, v54, v122
	v_add_f32_e32 v120, v120, v123
	v_add_f32_e32 v121, v121, v124
	v_lshl_add_u64 v[126:127], s[20:21], 0, v[50:51]
	s_and_saveexec_b64 s[22:23], s[0:1]
	s_cbranch_execz .LBB0_1100
	global_store_dword v[126:127], v54, off
	v_add_co_u32_e32 v128, vcc, 0x2000, v126
	s_nop 1
	v_addc_co_u32_e32 v129, vcc, 0, v127, vcc
	global_store_dword v[128:129], v120, off offset:1024
	v_add_co_u32_e32 v128, vcc, 0x4000, v126
	s_nop 1
	v_addc_co_u32_e32 v129, vcc, 0, v127, vcc
	global_store_dword v[128:129], v121, off offset:2048
	s_branch .LBB0_1100

; __device__ __forceinline__ float wave_sum(float v) {
; #pragma unroll
;     for (int o = 1; o < 64; o <<= 1) v += __shfl_xor(v, o);
;     return v;
; }
; __device__ __forceinline__ void bias_rows(const bf16_t* Wt, int N, const float* sh  , float* bias  , int gwi, int ngw, int lane) {
;     ...
;     for (int n = gwi; n < N; n += ngw) {
;         const u32x4 w0 = *(const u32x4*)(Wt + (size_t)n * DM + 8 * lane), w1 = *(const u32x4*)(Wt + (size_t)n * DM + 512 + 8 * lane);
;         float wf[16];
; #pragma unroll
;         for (int j = 0; j < 4; ++j) { wf[2 * j] = __uint_as_float(w0[j] << 16); wf[2 * j + 1] = __uint_as_float(w0[j] & 0xffff0000u); wf[8 + 2 * j] = __uint_as_float(w1[j] << 16); wf[8 + 2 * j + 1] = __uint_as_float(w1[j] & 0xffff0000u); }
; #pragma unroll
;         for (int v = 0; v < 3; ++v) {
;             float a = 0.f;
; #pragma unroll
;             for (int j = 0; j < 16; ++j) a += wf[j] * s[v][j >> 2][j & 3];
;             a = wave_sum(a);
;             if (lane == 0) bias[(size_t)v * N + n] = a;
;         }
;     }
.LBB0_1110:
	global_load_dwordx4 v[74:77], v[52:53], off offset:-1024
	global_load_dwordx4 v[78:81], v[52:53], off
	s_waitcnt vmcnt(0)
	v_lshlrev_b32_e32 v73, 16, v74
	v_and_b32_e32 v69, 0xffff0000, v74
	v_fma_f32 v54, v36, v73, 0
	v_lshlrev_b32_e32 v74, 16, v75
	v_fmac_f32_e32 v54, v37, v69
	v_and_b32_e32 v70, 0xffff0000, v75
	v_fmac_f32_e32 v54, v38, v74
	v_lshlrev_b32_e32 v75, 16, v76
	v_fmac_f32_e32 v54, v39, v70
	v_and_b32_e32 v71, 0xffff0000, v76
	v_fmac_f32_e32 v54, v44, v75
	v_lshlrev_b32_e32 v76, 16, v77
	v_fmac_f32_e32 v54, v45, v71
	v_and_b32_e32 v72, 0xffff0000, v77
	v_fmac_f32_e32 v54, v46, v76
	s_waitcnt lgkmcnt(0)
	v_lshlrev_b32_e32 v65, 16, v78
	v_fmac_f32_e32 v54, v47, v72
	v_and_b32_e32 v49, 0xffff0000, v78
	v_fmac_f32_e32 v54, v40, v65
	v_lshlrev_b32_e32 v66, 16, v79
	v_fmac_f32_e32 v54, v41, v49
	v_and_b32_e32 v56, 0xffff0000, v79
	v_fmac_f32_e32 v54, v42, v66
	v_lshlrev_b32_e32 v67, 16, v80
	v_fmac_f32_e32 v54, v43, v56
	v_and_b32_e32 v63, 0xffff0000, v80
	v_fmac_f32_e32 v54, v28, v67
	v_lshlrev_b32_e32 v68, 16, v81
	v_fmac_f32_e32 v54, v29, v63
	v_and_b32_e32 v64, 0xffff0000, v81
	v_fmac_f32_e32 v54, v30, v68
	v_fmac_f32_e32 v54, v31, v64
	v_fma_f32 v120, v20, v73, 0
	v_fmac_f32_e32 v120, v21, v69
	v_fmac_f32_e32 v120, v22, v74
	v_fmac_f32_e32 v120, v23, v70
	v_fmac_f32_e32 v120, v32, v75
	v_fmac_f32_e32 v120, v33, v71
	v_fmac_f32_e32 v120, v34, v76
	v_fmac_f32_e32 v120, v35, v72
	v_fmac_f32_e32 v120, v16, v65
	v_fmac_f32_e32 v120, v17, v49
	v_fmac_f32_e32 v120, v18, v66
	v_fmac_f32_e32 v120, v19, v56
	v_fmac_f32_e32 v120, v12, v67
	v_fmac_f32_e32 v120, v13, v63
	v_fmac_f32_e32 v120, v14, v68
	v_fmac_f32_e32 v120, v15, v64
	v_fma_f32 v121, v4, v73, 0
	v_fmac_f32_e32 v121, v5, v69
	v_fmac_f32_e32 v121, v6, v74
	v_fmac_f32_e32 v121, v7, v70
	v_fmac_f32_e32 v121, v8, v75
	v_fmac_f32_e32 v121, v9, v71
	v_fmac_f32_e32 v121, v10, v76
	v_fmac_f32_e32 v121, v11, v72
	v_fmac_f32_e32 v121, v0, v65
	v_fmac_f32_e32 v121, v1, v49
	v_fmac_f32_e32 v121, v2, v66
	v_fmac_f32_e32 v121, v3, v56
	v_fmac_f32_e32 v121, v24, v67
	v_fmac_f32_e32 v121, v25, v63
	v_fmac_f32_e32 v121, v26, v68
	v_fmac_f32_e32 v121, v27, v64
	ds_bpermute_b32 v122, v57, v54
	ds_bpermute_b32 v123, v57, v120
	ds_bpermute_b32 v124, v57, v121
	s_waitcnt lgkmcnt(0)
	v_add_f32_e32 v54, v54, v122
	v_add_f32_e32 v120, v120, v123
	v_add_f32_e32 v121, v121, v124
	ds_bpermute_b32 v122, v58, v54
	ds_bpermute_b32 v123, v58, v120
	ds_bpermute_b32 v124, v58, v121
	s_waitcnt lgkmcnt(0)
	v_add_f32_e32 v54, v54, v122
	v_add_f32_e32 v120, v120, v123
	v_add_f32_e32 v121, v121, v124
	ds_bpermute_b32 v122, v59, v54
	ds_bpermute_b32 v123, v59, v120
	ds_bpermute_b32 v124, v59, v121
	s_waitcnt lgkmcnt(0)
	v_add_f32_e32 v54, v54, v122
	v_add_f32_e32 v120, v120, v123
	v_add_f32_e32 v121, v121, v124
	ds_bpermute_b32 v122, v60, v54
	ds_bpermute_b32 v123, v60, v120
	ds_bpermute_b32 v124, v60, v121
	s_waitcnt lgkmcnt(0)
	v_add_f32_e32 v54, v54, v122
	v_add_f32_e32 v120, v120, v123
	v_add_f32_e32 v121, v121, v124
	ds_bpermute_b32 v122, v61, v54
	ds_bpermute_b32 v123, v61, v120
	ds_bpermute_b32 v124, v61, v121
	s_waitcnt lgkmcnt(0)
	v_add_f32_e32 v54, v54, v122
	v_add_f32_e32 v120, v120, v123
	v_add_f32_e32 v121, v121, v124
	ds_bpermute_b32 v122, v62, v54
	ds_bpermute_b32 v123, v62, v120
	ds_bpermute_b32 v124, v62, v121
	s_waitcnt lgkmcnt(0)
	v_add_f32_e32 v54, v54, v122
	v_add_f32_e32 v120, v120, v123
	v_add_f32_e32 v121, v121, v124
	v_lshl_add_u64 v[126:127], s[18:19], 0, v[50:51]
	s_and_saveexec_b64 s[20:21], s[0:1]
	s_cbranch_execz .LBB0_1109
	global_store_dword v[126:127], v54, off
	v_add_co_u32_e32 v128, vcc, 0x5000, v126
	s_nop 1
	v_addc_co_u32_e32 v129, vcc, 0, v127, vcc
	global_store_dword v[128:129], v120, off offset:2048
	v_add_co_u32_e32 v128, vcc, 0xb000, v126
	s_nop 1
	v_addc_co_u32_e32 v129, vcc, 0, v127, vcc
	global_store_dword v[128:129], v121, off
	s_branch .LBB0_1109
